# attention: bias row pre-shifted by a workgroup-uniform softmax reference, key-bias loaded straight into the next QK accumulators (32 VALU subs per step removed) on top of P4 load hoisting
# speedup vs baseline: 1.0088x; 1.0021x over previous
; __device__ __forceinline__ float qk_bound(const float* q_g, const float* k_g, int lane) {
;     float gq = fabsf(q_g[lane]), gk = fabsf(k_g[lane]);
; #pragma unroll
;     for (int o = 1; o < 64; o <<= 1) { gq = fmaxf(gq, __shfl_xor(gq, o)); gk = fmaxf(gk, __shfl_xor(gk, o)); }
;     return attn_body::C2 * 64.0f * 1.02f * gq * gk;
; }
; template <int LO, int HI> __global__ void __launch_bounds__(NWAVES * 64, 2) fox_fwd(Args args) {
;     ...
;         const float qkb = qk_bound(q_g, k_g, lane);
;         const attn_body::AttnTensors AT{ws, WS_Q, WS_K, WS_V, WS_SZA, WS_LF, WS_OAB, WS_BIAS, WS_J0, 2.0f * qkb + GAP_EXTRA, qkb};
;         const ConvItems CI{L};
;         attn_body::attn_phase_dyn<-1, ConvItems>((char*)lds + RING_OFF, AT, (unsigned*)(ws + WS_CTL) + CW_ATTNQ, CI, N_CONV_ITEMS);
.LBB0_337:
	s_or_b64 exec, exec, s[4:5]
	s_mov_b64 s[4:5], s[0:1]
	s_waitcnt lgkmcnt(0)
	s_barrier
	v_mov_b32_e32 v2, v0
	s_mov_b32 s3, s2
	s_load_dwordx4 s[8:11], s[4:5], 0x38
	s_load_dwordx2 s[6:7], s[4:5], 0x70
	s_load_dword s3, s[24:25], 0x0
	v_and_b32_e32 v2, 63, v2
	v_lshlrev_b32_e32 v2, 2, v2
	v_or_b32_e32 v8, 0xfffffe00, v0
	s_waitcnt lgkmcnt(0)
	s_add_u32 s86, s6, 0x1c000000
	s_addc_u32 s87, s7, 0
	s_mov_b32 s4, s3
	global_load_dword v3, v2, s[8:9]
	global_load_dword v4, v2, s[10:11]
	s_mov_b64 s[4:5], 0x1c100000
	s_mov_b64 s[8:9], 0x800
	s_waitcnt vmcnt(1)
	v_and_b32_e32 v2, 0x7fffffff, v3
	s_waitcnt vmcnt(0)
	v_and_b32_e32 v5, 0x7fffffff, v4
	ds_bpermute_b32 v2, v165, v2
	ds_bpermute_b32 v5, v165, v5
	v_max_f32_e64 v3, |v3|, |v3|
	v_max_f32_e64 v4, |v4|, |v4|
	s_waitcnt lgkmcnt(1)
	v_max_f32_e32 v2, v2, v2
	s_waitcnt lgkmcnt(0)
	v_max_f32_e32 v5, v5, v5
	v_max_f32_e32 v2, v3, v2
	v_max_f32_e32 v3, v4, v5
	ds_bpermute_b32 v4, v169, v2
	ds_bpermute_b32 v5, v169, v3
	s_waitcnt lgkmcnt(1)
	v_max_f32_e32 v4, v4, v4
	s_waitcnt lgkmcnt(0)
	v_max_f32_e32 v5, v5, v5
	v_max_f32_e32 v2, v2, v4
	v_max_f32_e32 v3, v3, v5
	ds_bpermute_b32 v4, v168, v2
	ds_bpermute_b32 v5, v168, v3
	s_waitcnt lgkmcnt(1)
	v_max_f32_e32 v4, v4, v4
	s_waitcnt lgkmcnt(0)
	v_max_f32_e32 v5, v5, v5
	v_max_f32_e32 v4, v2, v4
	v_max_f32_e32 v5, v3, v5
	ds_bpermute_b32 v6, v167, v4
	ds_bpermute_b32 v7, v167, v5
	v_lshlrev_b32_e32 v2, 2, v0
	v_mov_b32_e32 v3, 0
	v_add_u32_e32 v9, 0, v2
	s_waitcnt lgkmcnt(1)
	v_max_f32_e32 v6, v6, v6
	s_waitcnt lgkmcnt(0)
	v_max_f32_e32 v7, v7, v7
	v_max_f32_e32 v4, v4, v6
	v_max_f32_e32 v6, v5, v7
	ds_bpermute_b32 v5, v166, v4
	ds_bpermute_b32 v7, v166, v6
	v_lshl_add_u64 v[2:3], s[6:7], 0, v[2:3]
	v_add_u32_e32 v9, 0x18800, v9
	v_lshl_add_u64 v[2:3], v[2:3], 0, s[4:5]
	s_waitcnt lgkmcnt(1)
	v_max_f32_e32 v5, v5, v5
	s_waitcnt lgkmcnt(0)
	v_max_f32_e32 v7, v7, v7
	v_max_f32_e32 v5, v4, v5
	v_max_f32_e32 v4, v6, v7
	ds_bpermute_b32 v7, v164, v5
	ds_bpermute_b32 v6, v164, v4
	s_mov_b64 s[4:5], 0

; template<int THRL> __device__ __forceinline__ void attn_unit(int b,int h,int qb,int j0,f32x4v brow0,f32x4v brow1,unsigned*ctr,unsigned&nxt,const AttnTensors&T_,char*shm){
;   const bf16*Q=(const bf16*)(T_.ws+T_.oq); const bf16*__restrict__ K=(const bf16*)(T_.ws+T_.ok); const bf16*__restrict__ V=(const bf16*)(T_.ws+T_.ov);
;   const int tid=threadIdx.x,lane=tid&63,r32=lane&31,hi=lane>>5; const int wid=__builtin_amdgcn_readfirstlane(tid>>6);
;   const long rowbase=(long)b*SEQ; const int q0=qb*QB;
;   const bf16*Qw=Q+(rowbase+q0+wid*QBLK)*DM+h*D;
;   const bf16*Kh=K+(rowbase+(long)j0*KVBLK)*DM+h*D,*Vh=V+(rowbase+(long)j0*KVBLK)*DM+h*D;
;   const unsigned lds0=(unsigned)(uintptr_t)shm;
;   float*wsf=(float*)(shm+LDS_WS)+wid*64;
;   const bf16*ksrc=Kh+(long)lane*DM+wid*8;
;   const bf16*vsrc=Vh+(long)(16*(wid&3)+(lane>>2))*DM+(wid>>2)*32+(lane&3)*8;
;   const unsigned kdst=lds0+LDS_K+wid*1024, vdst=lds0+LDS_V+wid*1024;
;     ...
;   const int vb0=(int)(lds0+LDS_V)+((lane>>4)&1)*32+(lane&3)*8+(4*hi+((lane&15)>>2))*64;
;   const char*Kbase=shm+LDS_K; bf16x8 kf[8];
;   const lds_cptr shm3=(lds_cptr)shm; const lds_cptr kp0=shm3+LDS_K+hi*1024+r32*16; const lds_cptr vp0=shm3+LDS_V+((lane>>4)&1)*32+(lane&3)*8+(4*hi+((lane&15)>>2))*64;
;   const int NT=(q0+QB)/KVBLK-j0;
;   DMA_K(0,0);DMA_V(0,0);DMA_K(1,SLOTB);
;   bf16x8 qr[4];
;   #pragma unroll
; template<int THRL,class Extra> __device__ __forceinline__ void attn_phase_dyn(char*lds,const AttnTensors&T,unsigned*ctr,const Extra&X,int nextra){
;     ...
;     if(tid==0){uw[0]=nxt;}
;     asm volatile("s_waitcnt lgkmcnt(0)\n\ts_barrier":::"memory");
;     const unsigned u=(unsigned)__builtin_amdgcn_readfirstlane((int)uw[0]);
;     if(u>=(unsigned)(BATCH*NHEAD*NQB+nextra))break;
;     if(u>=(unsigned)(BATCH*NHEAD*NQB)){ if(tid==0)nxt=G_+__hip_atomic_fetch_add(ctr,1u,__ATOMIC_RELAXED,__HIP_MEMORY_SCOPE_AGENT);
;       X((int)u-BATCH*NHEAD*NQB); asm volatile("s_waitcnt lgkmcnt(0)\n\ts_barrier":::"memory"); continue; }
;     const int qb=NQB-1-(int)(u/(BATCH*NHEAD)), bh=(int)(u%(BATCH*NHEAD));
;     const int j0=__builtin_amdgcn_readfirstlane((int)jt[bh*NQB+qb]);
;     const f32x4v*src=(const f32x4v*)((const float*)(T.ws+T.obias)+(long)bh*SEQ)+tid*2; const f32x4v ba=src[0],bb=src[1];
;     attn_unit<THRL>(bh/NHEAD,bh%NHEAD,qb,j0,ba,bb,ctr,nxt,T,lds);
.LBB0_343:
	s_and_saveexec_b64 s[6:7], s[18:19]
	ds_write_b32 v201, v213 offset:49152
	s_or_b64 exec, exec, s[6:7]
	s_waitcnt lgkmcnt(0)
	s_barrier
	ds_read_b32 v1, v201 offset:49152
	s_mov_b64 s[6:7], -1
	s_waitcnt lgkmcnt(0)
	v_readfirstlane_b32 s63, v1
	s_cmpk_gt_u32 s63, 0x57f
	s_cbranch_scc1 .LBB0_342
	s_cmpk_lt_u32 s63, 0x400
	s_cbranch_scc0 .LBB0_361
	s_and_b32 s6, s63, 63
	s_lshr_b32 s44, s63, 6
	s_lshl_b32 s7, s6, 6
	s_add_i32 s7, s7, 0
	s_lshl_b32 s8, s44, 2
	s_sub_i32 s7, s7, s8
	s_add_i32 s7, s7, 0x1883c
	s_lshl_b32 s12, s6, 14
	v_mov_b32_e32 v1, s7
	s_sub_i32 s7, 15, s44
	v_lshl_add_u64 v[6:7], v[208:209], 0, s[12:13]
	s_bfe_u32 s12, s63, 0x30003
	v_readfirstlane_b32 s66, v0
	s_lshr_b32 s65, s66, 6
	s_lshl_b32 s8, s12, 12
	s_lshl_b32 s45, s7, 8
	s_or_b32 s7, s45, s8
	s_lshl_b32 s69, s65, 5
	s_add_i32 s10, s7, s69
	s_mov_b32 s11, s13
	ds_read_b32 v1, v1
	s_lshl_b64 s[8:9], s[10:11], 10
	s_add_u32 s7, s47, s8
	s_addc_u32 s9, s48, s9
	s_lshl_b32 s8, s63, 6
	s_and_b32 s8, s8, 0x1c0
	s_lshl_b32 s64, s8, 1
	s_waitcnt lgkmcnt(0)
	v_readfirstlane_b32 s6, v1
	s_add_u32 s8, s7, s64
	s_addc_u32 s9, s9, 0
	s_ashr_i32 s7, s6, 31
	s_lshl_b64 s[40:41], s[6:7], 15
	s_lshl_b32 s7, s12, 21
	s_add_u32 s40, s40, s7
	s_addc_u32 s41, s41, 0
	s_lshl_b64 s[40:41], s[40:41], 1
	s_add_u32 s7, s49, s40
	s_addc_u32 s12, s50, s41
	s_add_u32 s42, s7, s64
	s_addc_u32 s43, s12, 0
	s_add_u32 s7, s51, s40
	s_addc_u32 s12, s52, s41
	s_add_u32 s40, s7, s64
	s_addc_u32 s41, s12, 0
	s_lshr_b32 s7, s66, 2
	v_bfe_u32 v1, v0, 2, 4
	v_mov_b32_e32 v235, v201
	v_and_or_b32 v1, s7, 48, v1
	v_lshl_add_u64 v[10:11], s[42:43], 0, v[234:235]
	s_lshl_b32 s12, s65, 4
	v_lshlrev_b32_e32 v200, 10, v1
	v_lshl_add_u64 v[226:227], v[10:11], 0, s[12:13]
	v_lshl_add_u64 v[10:11], s[40:41], 0, v[200:201]
	s_and_b32 s12, s7, 0x3fffffc0
	v_lshl_add_u64 v[10:11], v[10:11], 0, s[12:13]
	s_lshl_b32 s12, s65, 10
	s_cmp_lg_u32 0, -1
	s_cselect_b32 s7, 0, 0
	global_load_dwordx4 v[2:5], v[6:7], off offset:16
	s_nop 0
	global_load_dwordx4 v[6:9], v[6:7], off
	s_and_b32 s88, s63, 63
	s_lshl_b32 s88, s88, 14
	s_lshl_b32 s89, s45, 2
	s_add_i32 s88, s88, s89
	s_addk_i32 s88, 0x200
	v_mov_b32_e32 v231, s88
	global_load_dword v231, v231, s[86:87]
	v_mov_b32_e32 v215, v201
	s_add_i32 s67, s12, s7
	s_mov_b32 s7, m0
	s_mov_b32 m0, s67
	s_nop 0
	global_load_lds_dwordx4 v[226:227], off
	s_mov_b32 m0, s7
	v_lshl_add_u64 v[228:229], v[10:11], 0, v[214:215]
	s_add_i32 s68, s67, 0x6000
	s_mov_b32 s7, m0
	s_mov_b32 m0, s68
	s_nop 0
	global_load_lds_dwordx4 v[228:229], off
	s_mov_b32 m0, s7
	v_lshl_add_u64 v[10:11], v[226:227], 0, s[16:17]
	s_add_i32 s7, s67, 0x2000
	s_mov_b32 s40, m0
	s_mov_b32 m0, s7
	s_nop 0
	global_load_lds_dwordx4 v[10:11], off
	s_mov_b32 m0, s40
	global_load_dwordx4 v[126:129], v255, s[8:9]
	global_load_dwordx4 v[122:125], v255, s[8:9] offset:32
	global_load_dwordx4 v[118:121], v255, s[8:9] offset:64
	global_load_dwordx4 v[114:117], v255, s[8:9] offset:96
	v_lshl_add_u64 v[10:11], v[226:227], 0, s[20:21]
	s_add_i32 s7, s67, 0x4000
	s_mov_b32 s8, m0
	s_mov_b32 m0, s7
	s_nop 0
	global_load_lds_dwordx4 v[10:11], off
	s_mov_b32 m0, s8
	v_add_u32_e32 v1, 0, v202
	v_add_u32_e32 v1, 0x14800, v1
	v_mov_b32_e32 v212, v213
	s_waitcnt vmcnt(4)
	v_add_f32_e32 v231, v237, v231
	v_sub_f32_e32 v2, v2, v231
	v_sub_f32_e32 v3, v3, v231
	v_sub_f32_e32 v4, v4, v231
	v_sub_f32_e32 v5, v5, v231
	v_sub_f32_e32 v6, v6, v231
	v_sub_f32_e32 v7, v7, v231
	v_sub_f32_e32 v8, v8, v231
	v_sub_f32_e32 v9, v9, v231
	ds_write_b128 v1, v[6:9]
	ds_write_b128 v1, v[2:5] offset:16
	s_and_saveexec_b64 s[8:9], s[18:19]
	s_cbranch_execz .LBB0_351
	s_mov_b64 s[42:43], exec
	v_mbcnt_lo_u32_b32 v1, s42, 0
	v_mbcnt_hi_u32_b32 v1, s43, v1
	v_cmp_eq_u32_e32 vcc, 0, v1
	s_and_saveexec_b64 s[40:41], vcc
	s_cbranch_execz .LBB0_350
	s_bcnt1_i32_b64 s7, s[42:43]
	v_mov_b32_e32 v2, s7
	global_atomic_add v2, v201, v2, s[14:15] sc0

; #define WAIT_BAR(N) asm volatile("s_waitcnt vmcnt(" #N ") lgkmcnt(0)\n\ts_barrier":::"memory")
;   #define BINIT(P0,P1,t) do{ _Pragma("unroll") for(int g_=0;g_<4;++g_){BL(P0,t,g_,0);BL(P1,t,g_,128);} _Pragma("unroll") for(int g_=0;g_<4;++g_){BS(P0,g_);BS(P1,g_);} }while(0)
;   #define CMASK(P0,P1,t) do{int jb_=(t)-(NT-4); if(jb_>=0)cmask(P0,P1,jb_,qrel,hi);}while(0)
;   #define CMASK(P0,P1,t) do{}while(0)
;   #define CMASK(P0,P1,t) do{int jb_=(t)-(NT-4); if(jb_>=0)cmask(P0,P1,jb_,qrel,hi);}while(0)
; __device__ __forceinline__ void cmask(f32x16&p0,f32x16&p1,int jb,int qrel,int hi){
;   const float NEG=-INFINITY; int kb=64*jb+4*hi;
;   #pragma unroll
;   for(int r=0;r<16;++r){int kv=kb+(r&3)+8*(r>>2); if(kv>qrel)p0[r]=NEG; if(kv+32>qrel)p1[r]=NEG;}
; }
; template<int THRL> __device__ __forceinline__ void attn_unit(int b,int h,int qb,int j0,f32x4v brow0,f32x4v brow1,unsigned*ctr,unsigned&nxt,const AttnTensors&T_,char*shm){
;     ...
;   if(tid==0)nxt=gridDim.x+__hip_atomic_fetch_add(ctr,1u,__ATOMIC_RELAXED,__HIP_MEMORY_SCOPE_AGENT);
;   WAIT_BAR(3);
;   mhat=((const __attribute__((address_space(3))) float*)(shm3+LDS_BIAS))[q0+qrel]+T_.hdr;
;   BINIT(pA0,pA1,0);
;   qkt(pA0,pA1,Kbase,qr,r32,hi);asm volatile("s_nop 15\n\ts_nop 7":"+v"(pA0),"+v"(pA1));CMASK(pA0,pA1,0);
.LBB0_351:
	s_or_b64 exec, exec, s[8:9]
	s_lshl_b32 s8, s45, 2
	v_or_b32_e32 v200, s69, v205
	s_add_i32 s8, s8, 0
	v_lshl_add_u32 v1, v200, 2, s8
	s_lshl_b32 s7, s6, 8
	s_waitcnt vmcnt(3) lgkmcnt(0)
	s_barrier
	v_add_u32_e32 v2, 0x14800, v1
	v_add_u32_e32 v1, s7, v240
	ds_read_b32 v18, v2
	ds_read_b128 v[2:5], v1
	ds_read_b128 v[6:9], v1 offset:32
	ds_read_b128 v[10:13], v1 offset:64
	ds_read_b128 v[34:37], v1 offset:128
	ds_read_b128 v[14:17], v1 offset:96
	ds_read_b128 v[38:41], v1 offset:160
	ds_read_b128 v[42:45], v1 offset:192
	ds_read_b128 v[46:49], v1 offset:224
	s_waitcnt lgkmcnt(8)
	v_mov_b32_e32 v230, 0
	s_waitcnt lgkmcnt(7)
	v_sub_f32_e32 v21, v5, v230
	v_sub_f32_e32 v20, v4, v230
	v_sub_f32_e32 v19, v3, v230
	v_sub_f32_e32 v18, v2, v230
	ds_read_b128 v[2:5], v207
	s_waitcnt lgkmcnt(6)
	v_sub_f32_e32 v29, v13, v230
	v_sub_f32_e32 v28, v12, v230
	v_sub_f32_e32 v27, v11, v230
	v_sub_f32_e32 v26, v10, v230
	s_waitcnt lgkmcnt(2)
	v_sub_f32_e32 v13, v45, v230
	v_sub_f32_e32 v12, v44, v230
	v_sub_f32_e32 v11, v43, v230
	v_sub_f32_e32 v10, v42, v230
	ds_read_b128 v[42:45], v207 offset:512
	v_sub_f32_e32 v33, v17, v230
	v_sub_f32_e32 v32, v16, v230
	v_sub_f32_e32 v31, v15, v230
	v_sub_f32_e32 v30, v14, v230
	v_sub_f32_e32 v25, v9, v230
	v_sub_f32_e32 v24, v8, v230
	v_sub_f32_e32 v23, v7, v230
	v_sub_f32_e32 v22, v6, v230
	s_waitcnt lgkmcnt(2)
	v_sub_f32_e32 v17, v49, v230
	v_sub_f32_e32 v16, v48, v230
	v_sub_f32_e32 v15, v47, v230
	v_sub_f32_e32 v14, v46, v230
	v_sub_f32_e32 v9, v41, v230
	s_waitcnt vmcnt(3) lgkmcnt(1)
	v_mfma_f32_32x32x16_bf16 v[18:33], v[2:5], v[126:129], v[18:33]
	v_sub_f32_e32 v8, v40, v230
	v_sub_f32_e32 v7, v39, v230
	v_sub_f32_e32 v6, v38, v230
	v_sub_f32_e32 v5, v37, v230
	v_sub_f32_e32 v4, v36, v230
	v_sub_f32_e32 v3, v35, v230
	v_sub_f32_e32 v2, v34, v230
	ds_read_b128 v[34:37], v207 offset:2048
	ds_read_b128 v[38:41], v207 offset:2560
	s_waitcnt lgkmcnt(2)
	v_mfma_f32_32x32x16_bf16 v[2:17], v[42:45], v[126:129], v[2:17]
	s_addk_i32 s45, 0x100
	s_lshr_b32 s8, s45, 6
	s_lshl_b64 s[40:41], s[10:11], 9
	s_sub_i32 s69, s8, s6
	s_cmp_gt_i32 s69, 4
	s_waitcnt vmcnt(2) lgkmcnt(1)
	v_mfma_f32_32x32x16_bf16 v[18:33], v[34:37], v[122:125], v[18:33]
	s_waitcnt lgkmcnt(0)
	v_mfma_f32_32x32x16_bf16 v[2:17], v[38:41], v[122:125], v[2:17]
	ds_read_b128 v[34:37], v207 offset:4096
	ds_read_b128 v[38:41], v207 offset:4608
	s_waitcnt vmcnt(1) lgkmcnt(1)
	v_mfma_f32_32x32x16_bf16 v[18:33], v[34:37], v[118:121], v[18:33]
	s_waitcnt lgkmcnt(0)
	v_mfma_f32_32x32x16_bf16 v[2:17], v[38:41], v[118:121], v[2:17]
	ds_read_b128 v[34:37], v207 offset:6144
	ds_read_b128 v[38:41], v207 offset:6656
	s_waitcnt vmcnt(0) lgkmcnt(1)
	v_mfma_f32_32x32x16_bf16 v[18:33], v[34:37], v[114:117], v[18:33]
	s_waitcnt lgkmcnt(0)
	v_mfma_f32_32x32x16_bf16 v[2:17], v[38:41], v[114:117], v[2:17]
	s_nop 15
	s_nop 7
	s_cbranch_scc1 .LBB0_353
	s_lshl_b32 s9, s69, 6
	v_subrev_u32_e32 v34, s9, v232
	v_add_u32_e32 v36, 0x120, v34
	v_add_u32_e32 v35, 0x100, v34
	v_cmp_le_i32_e32 vcc, v36, v200
	s_nop 5
	v_cndmask_b32_e32 v2, v252, v2, vcc
	v_cmp_lt_i32_e32 vcc, v35, v200
	s_nop 1
	v_cndmask_b32_e32 v19, v252, v19, vcc
	v_cmp_le_i32_e32 vcc, v35, v200
	v_add_u32_e32 v35, 0x121, v34
	s_nop 0
	v_cndmask_b32_e32 v18, v252, v18, vcc
	v_cmp_le_i32_e32 vcc, v35, v200
	v_add_u32_e32 v35, 0x102, v34
	s_nop 0
	v_cndmask_b32_e32 v3, v252, v3, vcc
	v_cmp_le_i32_e32 vcc, v35, v200
	v_add_u32_e32 v35, 0x122, v34
	s_nop 0
	v_cndmask_b32_e32 v20, v252, v20, vcc
	v_cmp_le_i32_e32 vcc, v35, v200
	v_add_u32_e32 v35, 0x103, v34
	s_nop 0
	v_cndmask_b32_e32 v4, v252, v4, vcc
	v_cmp_le_i32_e32 vcc, v35, v200
	v_add_u32_e32 v35, 0x123, v34
	s_nop 0
	v_cndmask_b32_e32 v21, v252, v21, vcc
	v_cmp_le_i32_e32 vcc, v35, v200
	v_add_u32_e32 v35, 0x108, v34
	s_nop 0
	v_cndmask_b32_e32 v5, v252, v5, vcc
	v_cmp_le_i32_e32 vcc, v35, v200
	v_add_u32_e32 v35, 0x128, v34
	s_nop 0
	v_cndmask_b32_e32 v22, v252, v22, vcc
	v_cmp_le_i32_e32 vcc, v35, v200
	v_add_u32_e32 v35, 0x109, v34
	s_nop 0
	v_cndmask_b32_e32 v6, v252, v6, vcc
	v_cmp_le_i32_e32 vcc, v35, v200
	v_add_u32_e32 v35, 0x129, v34
	s_nop 0
	v_cndmask_b32_e32 v23, v252, v23, vcc
	v_cmp_le_i32_e32 vcc, v35, v200
	v_add_u32_e32 v35, 0x10a, v34
	s_nop 0
	v_cndmask_b32_e32 v7, v252, v7, vcc
	v_cmp_le_i32_e32 vcc, v35, v200
	v_add_u32_e32 v35, 0x12a, v34
	s_nop 0
	v_cndmask_b32_e32 v24, v252, v24, vcc
	v_cmp_le_i32_e32 vcc, v35, v200
	v_add_u32_e32 v35, 0x10b, v34
	s_nop 0
	v_cndmask_b32_e32 v8, v252, v8, vcc
	v_cmp_le_i32_e32 vcc, v35, v200
	v_add_u32_e32 v35, 0x12b, v34
	s_nop 0
	v_cndmask_b32_e32 v25, v252, v25, vcc
	v_cmp_le_i32_e32 vcc, v35, v200
	v_add_u32_e32 v35, 0x110, v34
	s_nop 0
	v_cndmask_b32_e32 v9, v252, v9, vcc
	v_cmp_le_i32_e32 vcc, v35, v200
	v_add_u32_e32 v35, 0x130, v34
	s_nop 0
	v_cndmask_b32_e32 v26, v252, v26, vcc
	v_cmp_le_i32_e32 vcc, v35, v200
	v_add_u32_e32 v35, 0x111, v34
	s_nop 0
	v_cndmask_b32_e32 v10, v252, v10, vcc
	v_cmp_le_i32_e32 vcc, v35, v200
	v_add_u32_e32 v35, 0x131, v34
	s_nop 0
	v_cndmask_b32_e32 v27, v252, v27, vcc
	v_cmp_le_i32_e32 vcc, v35, v200
	v_add_u32_e32 v35, 0x112, v34
	s_nop 0
	v_cndmask_b32_e32 v11, v252, v11, vcc
	v_cmp_le_i32_e32 vcc, v35, v200
	v_add_u32_e32 v35, 0x132, v34
	s_nop 0
	v_cndmask_b32_e32 v28, v252, v28, vcc
	v_cmp_le_i32_e32 vcc, v35, v200
	v_add_u32_e32 v35, 0x113, v34
	s_nop 0
	v_cndmask_b32_e32 v12, v252, v12, vcc
	v_cmp_le_i32_e32 vcc, v35, v200
	v_add_u32_e32 v35, 0x133, v34
	s_nop 0
	v_cndmask_b32_e32 v29, v252, v29, vcc
	v_cmp_le_i32_e32 vcc, v35, v200
	v_add_u32_e32 v35, 0x118, v34
	s_nop 0
	v_cndmask_b32_e32 v13, v252, v13, vcc
	v_cmp_le_i32_e32 vcc, v35, v200
	v_add_u32_e32 v35, 0x138, v34
	s_nop 0
	v_cndmask_b32_e32 v30, v252, v30, vcc
	v_cmp_le_i32_e32 vcc, v35, v200
	v_add_u32_e32 v35, 0x119, v34
	s_nop 0
	v_cndmask_b32_e32 v14, v252, v14, vcc
	v_cmp_le_i32_e32 vcc, v35, v200
	v_add_u32_e32 v35, 0x139, v34
	s_nop 0
	v_cndmask_b32_e32 v31, v252, v31, vcc
	v_cmp_le_i32_e32 vcc, v35, v200
	v_add_u32_e32 v35, 0x11a, v34
	s_nop 0
	v_cndmask_b32_e32 v15, v252, v15, vcc
	v_cmp_le_i32_e32 vcc, v35, v200
	v_add_u32_e32 v35, 0x13a, v34
	s_nop 0
	v_cndmask_b32_e32 v32, v252, v32, vcc
	v_cmp_le_i32_e32 vcc, v35, v200
	v_add_u32_e32 v35, 0x11b, v34
	v_add_u32_e32 v34, 0x13b, v34
	v_cndmask_b32_e32 v16, v252, v16, vcc
	v_cmp_le_i32_e32 vcc, v35, v200
	s_nop 1
	v_cndmask_b32_e32 v33, v252, v33, vcc
	v_cmp_le_i32_e32 vcc, v34, v200
	s_nop 1
	v_cndmask_b32_e32 v17, v252, v17, vcc

; #define WAIT_BAR(N) asm volatile("s_waitcnt vmcnt(" #N ") lgkmcnt(0)\n\ts_barrier":::"memory")
;   #define RESC() do{ if(resc){ asm volatile("s_waitcnt lgkmcnt(0)":::"memory"); \
;       _Pragma("unroll") for(int d_=0;d_<2;++d_) _Pragma("unroll") for(int r=0;r<16;++r)o[d_][r]*=wsf[crow(r,hi)]; } }while(0)
;   #define ROT() do{sl_prev=sl_cur;sl_cur=sl_next;sl_next=(sl_next==(NSLOT-1)*SLOTB)?0:sl_next+SLOTB;}while(0)
; template<int THRL> __device__ __forceinline__ void attn_unit(int b,int h,int qb,int j0,f32x4v brow0,f32x4v brow1,unsigned*ctr,unsigned&nxt,const AttnTensors&T_,char*shm){
;     ...
;   for(;t+5<NT;t+=2){
;     STEP(pB0,pB1,pA0,pA1,t,true,true,true);     WAIT_BAR(2); RESC(); ROT();
;     STEP(pA0,pA1,pB0,pB1,t+1,true,true,true);   WAIT_BAR(2); RESC(); ROT();
.LBB0_355:
	s_mov_b32 s9, s71
	s_mov_b32 s12, s45
	s_mov_b32 s42, s70
	v_add_u32_e32 v35, s43, v239
	ds_read_b64_tr_b16 v[36:37], v35 offset:24576
	ds_read_b64_tr_b16 v[38:39], v35 offset:25088
	v_mfma_f32_32x32x16_bf16 v[66:81], v[174:177], v[126:129], v[66:81]
	v_add_f32_e32 v40, v98, v99
	v_add_f32_e32 v40, v100, v40
	v_add_f32_e32 v40, v101, v40
	v_add_f32_e32 v40, v102, v40
	v_add_f32_e32 v44, v103, v40
	v_cvt_pk_bf16_f32 v142, v98, v99
	v_cvt_pk_bf16_f32 v143, v100, v101
	ds_read_b64_tr_b16 v[40:41], v35 offset:28672
	ds_read_b64_tr_b16 v[42:43], v35 offset:29184
	v_mfma_f32_32x32x16_bf16 v[50:65], v[170:173], v[126:129], v[50:65]
	v_add_f32_e32 v44, v104, v44
	v_add_f32_e32 v44, v105, v44
	v_add_f32_e32 v44, v106, v44
	v_add_f32_e32 v48, v107, v44
	v_cvt_pk_bf16_f32 v144, v102, v103
	v_cvt_pk_bf16_f32 v145, v104, v105
	ds_read_b64_tr_b16 v[44:45], v35 offset:25600
	ds_read_b64_tr_b16 v[46:47], v35 offset:26112
	v_mfma_f32_32x32x16_bf16 v[66:81], v[166:169], v[122:125], v[66:81]
	v_add_f32_e32 v48, v108, v48
	v_add_f32_e32 v48, v109, v48
	v_add_f32_e32 v48, v110, v48
	v_add_f32_e32 v48, v111, v48
	v_cvt_pk_bf16_f32 v138, v106, v107
	v_cvt_pk_bf16_f32 v139, v108, v109
	ds_read_b64_tr_b16 v[98:99], v35 offset:29696
	ds_read_b64_tr_b16 v[100:101], v35 offset:30208
	v_mfma_f32_32x32x16_bf16 v[50:65], v[162:165], v[122:125], v[50:65]
	v_add_f32_e32 v48, v112, v48
	v_add_f32_e32 v48, v113, v48
	v_add_f32_e32 v48, v82, v48
	v_add_f32_e32 v48, v83, v48
	v_cvt_pk_bf16_f32 v140, v110, v111
	v_cvt_pk_bf16_f32 v141, v112, v113
	ds_read_b64_tr_b16 v[102:103], v35 offset:26624
	ds_read_b64_tr_b16 v[104:105], v35 offset:27136
	v_mfma_f32_32x32x16_bf16 v[66:81], v[158:161], v[118:121], v[66:81]
	v_add_f32_e32 v48, v84, v48
	v_add_f32_e32 v48, v85, v48
	v_add_f32_e32 v48, v86, v48
	v_add_f32_e32 v48, v87, v48
	v_cvt_pk_bf16_f32 v134, v82, v83
	v_cvt_pk_bf16_f32 v135, v84, v85
	ds_read_b64_tr_b16 v[106:107], v35 offset:30720
	ds_read_b64_tr_b16 v[108:109], v35 offset:31232
	v_mfma_f32_32x32x16_bf16 v[50:65], v[154:157], v[118:121], v[50:65]
	v_add_f32_e32 v48, v88, v48
	v_add_f32_e32 v48, v89, v48
	v_add_f32_e32 v48, v90, v48
	v_add_f32_e32 v48, v91, v48
	v_cvt_pk_bf16_f32 v136, v86, v87
	v_cvt_pk_bf16_f32 v137, v88, v89
	ds_read_b64_tr_b16 v[86:87], v35 offset:27648
	ds_read_b64_tr_b16 v[88:89], v35 offset:28160
	v_mfma_f32_32x32x16_bf16 v[66:81], v[150:153], v[114:117], v[66:81]
	v_add_f32_e32 v48, v92, v48
	v_add_f32_e32 v48, v93, v48
	v_add_f32_e32 v48, v94, v48
	v_add_f32_e32 v48, v95, v48
	v_cvt_pk_bf16_f32 v130, v90, v91
	v_cvt_pk_bf16_f32 v131, v92, v93
	ds_read_b64_tr_b16 v[82:83], v35 offset:31744
	s_waitcnt lgkmcnt(14)
	ds_read_b64_tr_b16 v[84:85], v35 offset:32256
	v_mfma_f32_32x32x16_bf16 v[50:65], v[146:149], v[114:117], v[50:65]
	v_add_f32_e32 v35, v96, v48
	v_add_f32_e32 v35, v97, v35
	v_add_f32_e32 v35, 0, v35
	v_cvt_pk_bf16_f32 v132, v94, v95
	v_cvt_pk_bf16_f32 v133, v96, v97
	v_lshl_add_u64 v[48:49], v[180:181], 0, s[28:29]
	s_add_i32 s43, s70, s67
	s_mov_b32 s45, m0
	s_mov_b32 m0, s43
	s_nop 0
	global_load_lds_dwordx4 v[48:49], off
	s_mov_b32 m0, s45
	v_lshl_add_u64 v[48:49], v[178:179], 0, s[28:29]
	s_add_i32 s43, s71, s68
	s_mov_b32 s45, m0
	s_mov_b32 m0, s43
	s_nop 0
	global_load_lds_dwordx4 v[48:49], off
	s_mov_b32 m0, s45
	s_waitcnt lgkmcnt(14)
	v_mfma_f32_32x32x16_bf16 v[2:17], v[142:145], v[36:39], v[2:17]
	ds_read_b128 v[110:113], v1 offset:96
	s_waitcnt lgkmcnt(14)
	ds_read_b128 v[90:93], v1 offset:192
	v_exp_f32_e32 v66, v66
	v_exp_f32_e32 v67, v67
	v_exp_f32_e32 v68, v68
	v_exp_f32_e32 v69, v69
	s_waitcnt lgkmcnt(14)
	v_mfma_f32_32x32x16_bf16 v[18:33], v[142:145], v[40:43], v[18:33]
	ds_read_b128 v[94:97], v1 offset:224
	v_exp_f32_e32 v70, v70
	v_exp_f32_e32 v71, v71
	v_exp_f32_e32 v72, v72
	v_exp_f32_e32 v73, v73
	v_add_u32_e32 v36, s9, v207
	s_waitcnt lgkmcnt(14)
	ds_read_b128 v[158:161], v36
	s_waitcnt lgkmcnt(14)
	ds_read_b128 v[162:165], v36 offset:512
	v_mfma_f32_32x32x16_bf16 v[2:17], v[138:141], v[44:47], v[2:17]
	v_exp_f32_e32 v74, v74
	v_exp_f32_e32 v75, v75
	v_exp_f32_e32 v76, v76
	v_exp_f32_e32 v77, v77
	s_waitcnt lgkmcnt(14)
	ds_read_b128 v[174:177], v36 offset:2048
	s_waitcnt lgkmcnt(14)
	ds_read_b128 v[146:149], v36 offset:2560
	v_mfma_f32_32x32x16_bf16 v[18:33], v[138:141], v[98:101], v[18:33]
	s_waitcnt lgkmcnt(14)
	ds_read_b128 v[98:101], v1
	v_exp_f32_e32 v78, v78
	v_exp_f32_e32 v79, v79
	v_exp_f32_e32 v80, v80
	v_exp_f32_e32 v81, v81
	s_waitcnt lgkmcnt(14)
	ds_read_b128 v[150:153], v36 offset:4096
	s_waitcnt lgkmcnt(14)
	ds_read_b128 v[40:43], v36 offset:4608
	v_mfma_f32_32x32x16_bf16 v[2:17], v[134:137], v[102:105], v[2:17]
	s_waitcnt lgkmcnt(14)
	ds_read_b128 v[102:105], v1 offset:32
	v_exp_f32_e32 v50, v50
	v_exp_f32_e32 v51, v51
	v_exp_f32_e32 v52, v52
	v_exp_f32_e32 v53, v53
	s_waitcnt lgkmcnt(14)
	ds_read_b128 v[44:47], v36 offset:6144
	s_waitcnt lgkmcnt(14)
	ds_read_b128 v[36:39], v36 offset:6656
	v_mfma_f32_32x32x16_bf16 v[18:33], v[134:137], v[106:109], v[18:33]
	s_waitcnt lgkmcnt(14)
	ds_read_b128 v[106:109], v1 offset:64
	v_exp_f32_e32 v54, v54
	v_exp_f32_e32 v55, v55
	v_exp_f32_e32 v56, v56
	v_exp_f32_e32 v57, v57
	v_mfma_f32_32x32x16_bf16 v[2:17], v[130:133], v[86:89], v[2:17]
	s_waitcnt lgkmcnt(14)
	ds_read_b128 v[86:89], v1 offset:160
	v_exp_f32_e32 v58, v58
	v_exp_f32_e32 v59, v59
	v_exp_f32_e32 v60, v60
	v_exp_f32_e32 v61, v61
	v_mfma_f32_32x32x16_bf16 v[18:33], v[130:133], v[82:85], v[18:33]
	s_waitcnt lgkmcnt(14)
	ds_read_b128 v[82:85], v1 offset:128
	v_exp_f32_e32 v62, v62
	v_exp_f32_e32 v63, v63
	v_exp_f32_e32 v64, v64
	v_exp_f32_e32 v65, v65
	s_waitcnt vmcnt(2) lgkmcnt(0)
	s_barrier
; #define WAIT_BAR(N) asm volatile("s_waitcnt vmcnt(" #N ") lgkmcnt(0)\n\ts_barrier":::"memory")
;   #define RESC() do{ if(resc){ asm volatile("s_waitcnt lgkmcnt(0)":::"memory"); \
;       _Pragma("unroll") for(int d_=0;d_<2;++d_) _Pragma("unroll") for(int r=0;r<16;++r)o[d_][r]*=wsf[crow(r,hi)]; } }while(0)
;   #define ROT() do{sl_prev=sl_cur;sl_cur=sl_next;sl_next=(sl_next==(NSLOT-1)*SLOTB)?0:sl_next+SLOTB;}while(0)
; template<int THRL> __device__ __forceinline__ void attn_unit(int b,int h,int qb,int j0,f32x4v brow0,f32x4v brow1,unsigned*ctr,unsigned&nxt,const AttnTensors&T_,char*shm){
;     ...
;   for(;t+5<NT;t+=2){
;     STEP(pB0,pB1,pA0,pA1,t,true,true,true);     WAIT_BAR(2); RESC(); ROT();
;     STEP(pA0,pA1,pB0,pB1,t+1,true,true,true);   WAIT_BAR(2); RESC(); ROT();
	s_add_i32 s43, s71, 0x2000
	s_cmpk_lg_i32 s71, 0x4000
	s_cselect_b32 s70, s43, 0
	v_add_u32_e32 v166, s42, v239
	ds_read_b64_tr_b16 v[154:155], v166 offset:24576
	ds_read_b64_tr_b16 v[156:157], v166 offset:25088
	v_mfma_f32_32x32x16_bf16 v[98:113], v[158:161], v[126:129], v[98:113]
	v_add_f32_e32 v48, v66, v67
	v_add_f32_e32 v48, v68, v48
	v_add_f32_e32 v48, v69, v48
	v_add_f32_e32 v48, v70, v48
	v_add_f32_e32 v48, v71, v48
	v_cvt_pk_bf16_f32 v142, v66, v67
	v_cvt_pk_bf16_f32 v143, v68, v69
	ds_read_b64_tr_b16 v[66:67], v166 offset:28672
	ds_read_b64_tr_b16 v[68:69], v166 offset:29184
	v_mfma_f32_32x32x16_bf16 v[82:97], v[162:165], v[126:129], v[82:97]
	v_add_f32_e32 v48, v72, v48
	v_add_f32_e32 v48, v73, v48
	v_add_f32_e32 v48, v74, v48
	v_add_f32_e32 v48, v75, v48
	v_cvt_pk_bf16_f32 v144, v70, v71
	v_cvt_pk_bf16_f32 v145, v72, v73
	ds_read_b64_tr_b16 v[70:71], v166 offset:25600
	ds_read_b64_tr_b16 v[72:73], v166 offset:26112
	v_mfma_f32_32x32x16_bf16 v[98:113], v[174:177], v[122:125], v[98:113]
	v_add_f32_e32 v48, v76, v48
	v_add_f32_e32 v48, v77, v48
	v_add_f32_e32 v48, v78, v48
	v_add_f32_e32 v48, v79, v48
	v_cvt_pk_bf16_f32 v138, v74, v75
	v_cvt_pk_bf16_f32 v139, v76, v77
	ds_read_b64_tr_b16 v[74:75], v166 offset:29696
	ds_read_b64_tr_b16 v[76:77], v166 offset:30208
	v_mfma_f32_32x32x16_bf16 v[82:97], v[146:149], v[122:125], v[82:97]
	v_add_f32_e32 v48, v80, v48
	v_add_f32_e32 v48, v81, v48
	v_add_f32_e32 v48, v50, v48
	v_add_f32_e32 v48, v51, v48
	v_cvt_pk_bf16_f32 v140, v78, v79
	v_cvt_pk_bf16_f32 v141, v80, v81
	ds_read_b64_tr_b16 v[78:79], v166 offset:26624
	ds_read_b64_tr_b16 v[80:81], v166 offset:27136
	v_mfma_f32_32x32x16_bf16 v[98:113], v[150:153], v[118:121], v[98:113]
	v_add_f32_e32 v48, v52, v48
	v_add_f32_e32 v48, v53, v48
	v_add_f32_e32 v48, v54, v48
	v_add_f32_e32 v48, v55, v48
	v_cvt_pk_bf16_f32 v134, v50, v51
	v_cvt_pk_bf16_f32 v135, v52, v53
	ds_read_b64_tr_b16 v[182:183], v166 offset:30720
	ds_read_b64_tr_b16 v[184:185], v166 offset:31232
	v_mfma_f32_32x32x16_bf16 v[82:97], v[40:43], v[118:121], v[82:97]
	v_add_f32_e32 v48, v56, v48
	v_add_f32_e32 v48, v57, v48
	v_add_f32_e32 v48, v58, v48
	v_add_f32_e32 v52, v59, v48
	v_cvt_pk_bf16_f32 v136, v54, v55
	v_cvt_pk_bf16_f32 v137, v56, v57
	ds_read_b64_tr_b16 v[48:49], v166 offset:27648
	ds_read_b64_tr_b16 v[50:51], v166 offset:28160
	v_mfma_f32_32x32x16_bf16 v[98:113], v[44:47], v[114:117], v[98:113]
	v_add_f32_e32 v40, v60, v52
	v_add_f32_e32 v40, v61, v40
	v_add_f32_e32 v40, v62, v40
	v_add_f32_e32 v52, v63, v40
	v_cvt_pk_bf16_f32 v130, v58, v59
	v_cvt_pk_bf16_f32 v131, v60, v61
	ds_read_b64_tr_b16 v[40:41], v166 offset:31744
	s_waitcnt lgkmcnt(14)
	ds_read_b64_tr_b16 v[42:43], v166 offset:32256
	v_mfma_f32_32x32x16_bf16 v[82:97], v[36:39], v[114:117], v[82:97]
	v_add_f32_e32 v44, v64, v52
	v_add_f32_e32 v44, v65, v44
	v_add_f32_e32 v215, 0, v44
	v_cvt_pk_bf16_f32 v132, v62, v63
	v_cvt_pk_bf16_f32 v133, v64, v65
	s_add_i32 s42, s71, s67
	s_mov_b32 s43, m0
	s_mov_b32 m0, s42
	s_nop 0
	global_load_lds_dwordx4 v[180:181], off
	s_mov_b32 m0, s43
	s_add_i32 s42, s70, s68
	s_mov_b32 s43, m0
	s_mov_b32 m0, s42
	s_nop 0
	global_load_lds_dwordx4 v[178:179], off
	s_mov_b32 m0, s43
	s_waitcnt lgkmcnt(14)
	v_mfma_f32_32x32x16_bf16 v[2:17], v[142:145], v[154:157], v[2:17]
	ds_read_b128 v[54:57], v1 offset:416
	s_waitcnt lgkmcnt(14)
	ds_read_b128 v[58:61], v1 offset:448
	v_exp_f32_e32 v98, v98
	v_exp_f32_e32 v99, v99
	v_exp_f32_e32 v100, v100
	v_exp_f32_e32 v101, v101
	s_waitcnt lgkmcnt(14)
	v_mfma_f32_32x32x16_bf16 v[18:33], v[142:145], v[66:69], v[18:33]
	ds_read_b128 v[66:69], v1 offset:256
	v_exp_f32_e32 v102, v102
	v_exp_f32_e32 v103, v103
	v_exp_f32_e32 v104, v104
	v_exp_f32_e32 v105, v105
	v_add_u32_e32 v64, s70, v207
	s_waitcnt lgkmcnt(14)
	ds_read_b128 v[174:177], v64
	s_waitcnt lgkmcnt(14)
	ds_read_b128 v[170:173], v64 offset:512
	v_mfma_f32_32x32x16_bf16 v[2:17], v[138:141], v[70:73], v[2:17]
	s_waitcnt lgkmcnt(14)
	ds_read_b128 v[70:73], v1 offset:288
	v_exp_f32_e32 v106, v106
	v_exp_f32_e32 v107, v107
	v_exp_f32_e32 v108, v108
	v_exp_f32_e32 v109, v109
	s_waitcnt lgkmcnt(14)
	ds_read_b128 v[166:169], v64 offset:2048
	s_waitcnt lgkmcnt(14)
	ds_read_b128 v[162:165], v64 offset:2560
	v_mfma_f32_32x32x16_bf16 v[18:33], v[138:141], v[74:77], v[18:33]
	s_waitcnt lgkmcnt(14)
	ds_read_b128 v[74:77], v1 offset:320
	v_exp_f32_e32 v110, v110
	v_exp_f32_e32 v111, v111
	v_exp_f32_e32 v112, v112
	v_exp_f32_e32 v113, v113
	s_waitcnt lgkmcnt(14)
	ds_read_b128 v[158:161], v64 offset:4096
	s_waitcnt lgkmcnt(14)
	ds_read_b128 v[154:157], v64 offset:4608
	v_mfma_f32_32x32x16_bf16 v[2:17], v[134:137], v[78:81], v[2:17]
	s_waitcnt lgkmcnt(14)
	ds_read_b128 v[78:81], v1 offset:352
	v_exp_f32_e32 v82, v82
	v_exp_f32_e32 v83, v83
	v_exp_f32_e32 v84, v84
	v_exp_f32_e32 v85, v85
	s_waitcnt lgkmcnt(14)
	ds_read_b128 v[150:153], v64 offset:6144
	s_waitcnt lgkmcnt(14)
	ds_read_b128 v[146:149], v64 offset:6656
	v_mfma_f32_32x32x16_bf16 v[18:33], v[134:137], v[182:185], v[18:33]
	s_waitcnt lgkmcnt(14)
	ds_read_b128 v[62:65], v1 offset:480
	v_exp_f32_e32 v86, v86
	v_exp_f32_e32 v87, v87
	v_exp_f32_e32 v88, v88
	v_exp_f32_e32 v89, v89
	v_mfma_f32_32x32x16_bf16 v[2:17], v[130:133], v[48:51], v[2:17]
	s_waitcnt lgkmcnt(14)
	ds_read_b128 v[50:53], v1 offset:384
	v_exp_f32_e32 v90, v90
	v_exp_f32_e32 v91, v91
	v_exp_f32_e32 v92, v92
	v_exp_f32_e32 v93, v93
	v_mfma_f32_32x32x16_bf16 v[18:33], v[130:133], v[40:43], v[18:33]
	v_exp_f32_e32 v94, v94
	v_exp_f32_e32 v95, v95
	v_exp_f32_e32 v96, v96
	v_exp_f32_e32 v97, v97
	s_add_i32 s42, s70, 0x2000
	s_waitcnt vmcnt(2) lgkmcnt(0)
	s_barrier
	s_cmpk_lg_i32 s70, 0x4000
	v_add_f32_e32 v34, v34, v35
	s_mov_b32 s43, s71
	s_cselect_b32 s71, s42, 0
	s_add_i32 s45, s12, 2
	v_add_u32_e32 v1, 0x200, v1
	v_lshl_add_u64 v[178:179], v[178:179], 0, s[20:21]
	v_lshl_add_u64 v[180:181], v[180:181], 0, s[20:21]
	s_cmp_ge_i32 s45, s69
	v_add_f32_e32 v34, v34, v215
	s_cbranch_scc0 .LBB0_355
	s_add_i32 s12, s12, -3
	s_add_i32 s42, s12, 1
	s_cmp_ge_i32 s42, s69
	s_cbranch_scc0 .LBB0_370

; template <int LO, int HI> __global__ void __launch_bounds__(NWAVES * 64, 2) fox_fwd(Args args) {
;     extern __shared__ __attribute__((aligned(16))) unsigned char lds[];
	.amdhsa_kernel _Z7fox_fwdILi0ELi6EEv4Args
		.amdhsa_group_segment_fixed_size 0
		.amdhsa_private_segment_fixed_size 0
		.amdhsa_kernarg_size 376
		.amdhsa_user_sgpr_count 2
		.amdhsa_user_sgpr_dispatch_ptr 0
		.amdhsa_user_sgpr_queue_ptr 0
		.amdhsa_user_sgpr_kernarg_segment_ptr 1
		.amdhsa_user_sgpr_dispatch_id 0
		.amdhsa_user_sgpr_kernarg_preload_length 0
		.amdhsa_user_sgpr_kernarg_preload_offset 0
		.amdhsa_user_sgpr_private_segment_size 0
		.amdhsa_uses_dynamic_stack 0
		.amdhsa_enable_private_segment 0
		.amdhsa_system_sgpr_workgroup_id_x 1
		.amdhsa_system_sgpr_workgroup_id_y 0
		.amdhsa_system_sgpr_workgroup_id_z 0
		.amdhsa_system_sgpr_workgroup_info 0
		.amdhsa_system_vgpr_workitem_id 0
		.amdhsa_next_free_vgpr 256
		.amdhsa_next_free_sgpr 90
		.amdhsa_accum_offset 256
		.amdhsa_reserve_vcc 1
		.amdhsa_float_round_mode_32 0
		.amdhsa_float_round_mode_16_64 0
		.amdhsa_float_denorm_mode_32 3
		.amdhsa_float_denorm_mode_16_64 3
		.amdhsa_dx10_clamp 1
		.amdhsa_ieee_mode 1
		.amdhsa_fp16_overflow 0
		.amdhsa_tg_split 0
		.amdhsa_exception_fp_ieee_invalid_op 0
		.amdhsa_exception_fp_denorm_src 0
		.amdhsa_exception_fp_ieee_div_zero 0
		.amdhsa_exception_fp_ieee_overflow 0
		.amdhsa_exception_fp_ieee_underflow 0
		.amdhsa_exception_fp_ieee_inexact 0
		.amdhsa_exception_int_div_zero 0
	.end_amdhsa_kernel

; template <int LO, int HI> __global__ void __launch_bounds__(NWAVES * 64, 2) fox_fwd(Args args) {
;     extern __shared__ __attribute__((aligned(16))) unsigned char lds[];
amdhsa.kernels:
  - .agpr_count:     0
    .args:
      - .offset:         0
        .size:           120
        .value_kind:     by_value
      - .offset:         120
        .size:           4
        .value_kind:     hidden_block_count_x
      - .offset:         124
        .size:           4
        .value_kind:     hidden_block_count_y
      - .offset:         128
        .size:           4
        .value_kind:     hidden_block_count_z
      - .offset:         132
        .size:           2
        .value_kind:     hidden_group_size_x
      - .offset:         134
        .size:           2
        .value_kind:     hidden_group_size_y
      - .offset:         136
        .size:           2
        .value_kind:     hidden_group_size_z
      - .offset:         138
        .size:           2
        .value_kind:     hidden_remainder_x
      - .offset:         140
        .size:           2
        .value_kind:     hidden_remainder_y
      - .offset:         142
        .size:           2
        .value_kind:     hidden_remainder_z
      - .offset:         160
        .size:           8
        .value_kind:     hidden_global_offset_x
      - .offset:         168
        .size:           8
        .value_kind:     hidden_global_offset_y
      - .offset:         176
        .size:           8
        .value_kind:     hidden_global_offset_z
      - .offset:         184
        .size:           2
        .value_kind:     hidden_grid_dims
      - .offset:         240
        .size:           4
        .value_kind:     hidden_dynamic_lds_size
    .group_segment_fixed_size: 0
    .kernarg_segment_align: 8
    .kernarg_segment_size: 376
    .language:       OpenCL C
    .language_version:
      - 2
      - 0
    .max_flat_workgroup_size: 512
    .name:           _Z7fox_fwdILi0ELi6EEv4Args
    .private_segment_fixed_size: 0
    .sgpr_count:     96
    .sgpr_spill_count: 0
    .symbol:         _Z7fox_fwdILi0ELi6EEv4Args.kd
    .uniform_work_group_size: 1
    .uses_dynamic_stack: false
    .vgpr_count:     256
    .vgpr_spill_count: 0
    .wavefront_size: 64
